# scan producer: bias add + exp2 scale folded into v_fmamk with pre-scaled hoisted constants (14 fewer VALU per chunk), hazard pads re-derived
# baseline (speedup 1.0000x reference)
; __device__ __forceinline__ float sigmoidf_(float x) { return __builtin_amdgcn_rcpf(1.0f + __expf(-x)); }
; #define RW_ISSUE(CK) do { const int st_ = (CK) * TC + ptok; const int t_ = d ? (T - 1 - st_) : st_; const bf16_t* zr_ = rw_row(p.ws, b * T + t_); \
;             _Pragma("unroll") for (int g = 0; g < 5; ++g) rc[g] = *(const u32x4*)(zr_ + offs[g]); } while (0)
; __device__ void rw_scan(const Params& p, int l, unsigned char* shm, int item) {
;     ...
;     if (w >= 4) {
;         const int pw = w - 4, ptok = pw * 8 + (lane >> 3), sub = lane & 7;
;         const int r_ = lane & 15, kg = lane >> 4;
;         bf16x8 bfr[2][4][2];
; #pragma unroll
;         for (int mtx = 0; mtx < 2; ++mtx)
; #pragma unroll
;             for (int nt = 0; nt < 4; ++nt)
; #pragma unroll
;                 for (int ks2 = 0; ks2 < 2; ++ks2) bfr[mtx][nt][ks2] = *(const bf16x8*)(bfl + ((size_t)((mtx * 4 + nt) * 2 + ks2) * 64 + lane) * 16);
;         const int offs[5] = {h * 64 + sub * 8, 768 + h * 64 + sub * 8, 1536 + h * 64 + sub * 8, 2304 + d * 64 + sub * 8, 2432 + d * 64 + sub * 8};
;         u32x4 rc[5];
;         float* wl = wla + pw * 1024; float* al = wl + 512;
;     ...
;         RW_ISSUE(0);
;     ...
;                 for (int e = 0; e < 8; ++e) { const float wa = cst[sub * 8 + e] + (e < 4 ? wl0[e & 3] : wl1[e & 3]), aa = cst[64 + sub * 8 + e] + (e < 4 ? al0[e & 3] : al1[e & 3]);
;                     av[e] = sigmoidf_(aa); dec[e] = __expf(-0.6065306597126334f * sigmoidf_(wa)); kkv[e] = ks_[e] * cst[128 + sub * 8 + e]; ssq += kkv[e] * kkv[e];
.LBB0_306:
	s_andn2_saveexec_b64 s[10:11], s[0:1]
	s_cbranch_execz .LBB0_335
	v_add_u32_e32 v75, -4, v4
	v_and_b32_e32 v79, 7, v3
	v_lshrrev_b32_e32 v77, 3, v74
	v_lshlrev_b32_e32 v80, 3, v75
	v_lshlrev_b32_e32 v81, 3, v79
	s_mul_i32 s0, s9, 0x180000
	v_readlane_b32 s1, v253, 18
	v_or_b32_e32 v179, v80, v77
	v_lshl_or_b32 v0, s9, 6, v81
	s_add_u32 s13, s1, s0
	v_readlane_b32 s0, v253, 19
	v_or_b32_e32 v76, 0x900, v0
	v_or_b32_e32 v78, 0x980, v0
	v_sub_u32_e32 v0, 0x3fff, v179
	s_addc_u32 s16, s0, 0
	s_lshl_b32 s0, s8, 6
	v_cndmask_b32_e32 v0, v0, v179, vcc
	s_lshl_b32 s14, s2, 14
	v_or_b32_e32 v126, s0, v81
	s_add_i32 s1, s0, 0x300
	s_addk_i32 s0, 0x600
	v_add_u32_e32 v8, s14, v0
	v_mov_b64_e32 v[6:7], s[94:95]
	v_or_b32_e32 v128, s1, v81
	v_or_b32_e32 v142, s0, v81
	v_mad_i64_i32 v[6:7], s[0:1], v8, s22, v[6:7]
	s_mov_b64 s[0:1], 0xe504c00
	v_and_b32_e32 v0, 0x7f, v0
	v_lshl_add_u64 v[6:7], v[6:7], 0, s[0:1]
	s_movk_i32 s0, 0x7f
	v_cmp_eq_u32_e64 s[0:1], s0, v0
	v_readlane_b32 s2, v253, 20
	v_ashrrev_i32_e32 v8, 6, v8
	v_cndmask_b32_e64 v9, 0, 1, s[0:1]
	v_readlane_b32 s3, v253, 21
	v_and_or_b32 v10, v8, -2, v9
	v_ashrrev_i32_e32 v127, 31, v126
	v_mov_b64_e32 v[8:9], s[2:3]
	s_movk_i32 s2, 0x1500
	v_mad_i64_i32 v[8:9], s[2:3], v10, s2, v[8:9]
	v_cmp_eq_u32_e64 s[2:3], 0, v0
	s_or_b64 s[0:1], s[2:3], s[0:1]
	v_cndmask_b32_e64 v7, v7, v9, s[0:1]
	v_cndmask_b32_e64 v6, v6, v8, s[0:1]
	v_mov_b32_e32 v129, v1
	v_lshl_add_u64 v[8:9], v[126:127], 1, v[6:7]
	v_lshl_add_u64 v[10:11], v[128:129], 1, v[6:7]
	v_lshlrev_b32_e32 v0, 1, v76
	global_load_dwordx4 v[90:93], v[8:9], off
	global_load_dwordx4 v[98:101], v[10:11], off
	v_mov_b32_e32 v143, v1
	v_lshl_add_u64 v[10:11], v[6:7], 0, v[0:1]
	v_lshlrev_b32_e32 v0, 1, v78
	v_lshl_add_u64 v[8:9], v[142:143], 1, v[6:7]
	v_lshl_add_u64 v[6:7], v[6:7], 0, v[0:1]
	global_load_dwordx4 v[70:73], v[8:9], off
	global_load_dwordx4 v[86:89], v[10:11], off
	global_load_dwordx4 v[82:85], v[6:7], off
	v_lshlrev_b32_e32 v0, 4, v74
	v_add_u32_e32 v6, 0, v0
	v_add_u32_e32 v14, 0x17000, v6
	ds_read_b128 v[62:65], v14
	ds_read_b128 v[58:61], v14 offset:1024
	ds_read_b128 v[42:45], v14 offset:2048
	ds_read_b128 v[38:41], v14 offset:3072
	ds_read_b128 v[26:29], v14 offset:4096
	ds_read_b128 v[22:25], v14 offset:5120
	ds_read_b128 v[10:13], v14 offset:6144
	ds_read_b128 v[6:9], v14 offset:7168
	ds_read_b128 v[66:69], v14 offset:8192
	ds_read_b128 v[54:57], v14 offset:9216
	ds_read_b128 v[50:53], v14 offset:10240
	ds_read_b128 v[46:49], v14 offset:11264
	ds_read_b128 v[34:37], v14 offset:12288
	ds_read_b128 v[30:33], v14 offset:13312
	ds_read_b128 v[18:21], v14 offset:14336
	ds_read_b128 v[14:17], v14 offset:15360
	v_readlane_b32 s0, v253, 46
	v_add_lshl_u32 v80, v80, v2, 7
	v_lshlrev_b32_e32 v95, 7, v179
	v_lshl_add_u32 v75, v75, 12, s0
	v_readlane_b32 s0, v253, 47
	v_and_b32_e32 v80, 0xf80, v80
	v_lshlrev_b32_e32 v94, 5, v79
	v_add_u32_e32 v96, s0, v95
	v_add_u32_e32 v102, s0, v80
	s_movk_i32 s0, 0x100
	v_and_or_b32 v0, v0, s0, v2
	v_lshlrev_b32_e32 v2, 8, v77
	v_readlane_b32 s1, v253, 48
	v_add3_u32 v184, v75, v94, v2
	s_add_i32 s0, 0, 0x21000
	v_bfe_u32 v2, v3, 1, 2
	s_ashr_i32 s9, s8, 31
	v_add_u32_e32 v95, s1, v95
	v_add_u32_e32 v80, s1, v80
	v_add_u32_e32 v183, s0, v94
	v_cmp_eq_u32_e64 s[4:5], s12, v2
	v_lshlrev_b32_e32 v2, 3, v3
	s_lshl_b64 s[0:1], s[8:9], 2
	v_lshlrev_b32_e32 v97, 4, v79
	v_lshlrev_b32_e32 v180, 6, v179
	v_and_b32_e32 v181, 8, v2
	v_or_b32_e32 v2, s12, v79
	s_add_u32 s12, s13, s0
	v_lshl_or_b32 v190, v4, 3, v77
	s_mov_b32 s15, 0
	v_cmp_gt_u32_e64 s[6:7], 32, v74
	v_or_b32_e32 v182, v180, v81
	v_cmp_eq_u32_e64 s[2:3], 0, v2
	s_addc_u32 s13, s16, s1
	v_lshl_add_u32 v185, v0, 2, v75
	v_sub_u32_e32 v191, 0x3fff, v190
	v_lshlrev_b32_e32 v0, 1, v76
	v_lshlrev_b32_e32 v144, 1, v78
	v_add_u32_e32 v189, v96, v97
	v_add_u32_e32 v188, v95, v97
	v_add_u32_e32 v187, v102, v5
	v_add_u32_e32 v186, v80, v5
	s_mov_b32 s16, 0
	ds_read_b128 v[206:209], v183
	ds_read_b128 v[210:213], v183 offset:16
	ds_read_b128 v[214:217], v183 offset:256
	ds_read_b128 v[218:221], v183 offset:272
	ds_read_b128 v[222:225], v183 offset:512
	ds_read_b128 v[226:229], v183 offset:528
	ds_read_b128 v[230:233], v183 offset:768
	ds_read_b128 v[234:237], v183 offset:784
	ds_read_b128 v[238:241], v183 offset:1024
	ds_read_b128 v[242:245], v183 offset:1040
	s_waitcnt lgkmcnt(0)
	v_mul_f32_e32 v206, 0xbfb8aa3b, v206
	v_mul_f32_e32 v207, 0xbfb8aa3b, v207
	v_mul_f32_e32 v208, 0xbfb8aa3b, v208
	v_mul_f32_e32 v209, 0xbfb8aa3b, v209
	v_mul_f32_e32 v210, 0xbfb8aa3b, v210
	v_mul_f32_e32 v211, 0xbfb8aa3b, v211
	v_mul_f32_e32 v212, 0xbfb8aa3b, v212
	v_mul_f32_e32 v213, 0xbfb8aa3b, v213
	v_mul_f32_e32 v214, 0xbfb8aa3b, v214
	v_mul_f32_e32 v215, 0xbfb8aa3b, v215
	v_mul_f32_e32 v216, 0xbfb8aa3b, v216
	v_mul_f32_e32 v217, 0xbfb8aa3b, v217
	v_mul_f32_e32 v218, 0xbfb8aa3b, v218
	v_mul_f32_e32 v219, 0xbfb8aa3b, v219
	v_mul_f32_e32 v220, 0xbfb8aa3b, v220
	v_mul_f32_e32 v221, 0xbfb8aa3b, v221

; __device__ __forceinline__ float sigmoidf_(float x) { return __builtin_amdgcn_rcpf(1.0f + __expf(-x)); }
; __device__ void rw_scan(const Params& p, int l, unsigned char* shm, int item) {
;     ...
;                 const f32x4 wl0 = *(const f32x4*)(wl + tl * 64 + sub * 8), wl1 = *(const f32x4*)(wl + tl * 64 + sub * 8 + 4), al0 = *(const f32x4*)(al + tl * 64 + sub * 8), al1 = *(const f32x4*)(al + tl * 64 + sub * 8 + 4);
;                 float kkv[8], ssq = 0.f, av[8], dec[8], kd[8], bpart = 0.f;
; #pragma unroll
;                 for (int e = 0; e < 8; ++e) { const float wa = cst[sub * 8 + e] + (e < 4 ? wl0[e & 3] : wl1[e & 3]), aa = cst[64 + sub * 8 + e] + (e < 4 ? al0[e & 3] : al1[e & 3]);
;                     av[e] = sigmoidf_(aa); dec[e] = __expf(-0.6065306597126334f * sigmoidf_(wa)); kkv[e] = ks_[e] * cst[128 + sub * 8 + e]; ssq += kkv[e] * kkv[e];
;                     kd[e] = ks_[e] * (1.0f + (av[e] - 1.0f) * cst[192 + sub * 8 + e]); bpart += rs_[e] * kd[e] * cst[256 + sub * 8 + e]; }
.LBB0_316:
	s_or_b64 exec, exec, s[0:1]
	v_lshlrev_b32_e32 v146, 16, v98
	v_and_b32_e32 v147, 0xffff0000, v98
	v_lshlrev_b32_e32 v148, 16, v99
	v_and_b32_e32 v149, 0xffff0000, v99
	v_lshlrev_b32_e32 v158, 16, v100
	v_and_b32_e32 v159, 0xffff0000, v100
	v_lshlrev_b32_e32 v156, 16, v101
	v_and_b32_e32 v157, 0xffff0000, v101
	ds_read_b128 v[98:101], v184
	ds_read_b128 v[106:109], v184 offset:16
	ds_read_b128 v[102:105], v184 offset:2048
	ds_read_b128 v[110:113], v184 offset:2064
	v_lshlrev_b32_e32 v94, 16, v90
	s_waitcnt lgkmcnt(0)
	v_fmamk_f32 v102, v102, 0xbfb8aa3b, v214
	v_exp_f32_e32 v102, v102
	v_fmamk_f32 v104, v104, 0xbfb8aa3b, v216
	v_exp_f32_e32 v104, v104
	v_add_f32_e32 v102, 1.0, v102
	v_rcp_f32_e32 v150, v102
	v_fmamk_f32 v102, v103, 0xbfb8aa3b, v215
	v_exp_f32_e32 v102, v102
	v_add_f32_e32 v104, 1.0, v104
	v_and_b32_e32 v95, 0xffff0000, v90
	v_add_f32_e32 v102, 1.0, v102
	v_rcp_f32_e32 v151, v102
	v_lshlrev_b32_e32 v96, 16, v91
	v_pk_add_f32 v[102:103], v[150:151], -1.0 op_sel_hi:[1,0]
	s_waitcnt lgkmcnt(2)
	v_pk_fma_f32 v[102:103], v[230:231], v[102:103], 1.0 op_sel_hi:[1,1,0]
	v_and_b32_e32 v97, 0xffff0000, v91
	v_pk_mul_f32 v[102:103], v[102:103], v[146:147]
	s_nop 0
	v_mul_f32_e32 v118, v102, v94
	s_waitcnt lgkmcnt(1)
	v_fma_f32 v145, v238, v118, 0
	v_rcp_f32_e32 v152, v104
	v_fmamk_f32 v104, v105, 0xbfb8aa3b, v217
	v_exp_f32_e32 v104, v104
	v_mul_f32_e32 v118, v103, v95
	v_fmac_f32_e32 v145, v239, v118
	v_add_f32_e32 v104, 1.0, v104
	v_rcp_f32_e32 v153, v104
	s_nop 0
	v_pk_add_f32 v[104:105], v[152:153], -1.0 op_sel_hi:[1,0]
	v_lshlrev_b32_e32 v90, 16, v92
	v_pk_fma_f32 v[104:105], v[232:233], v[104:105], 1.0 op_sel_hi:[1,1,0]
	s_waitcnt lgkmcnt(1)
	v_fmamk_f32 v110, v110, 0xbfb8aa3b, v218
	v_exp_f32_e32 v110, v110
	v_fmamk_f32 v112, v112, 0xbfb8aa3b, v220
	v_exp_f32_e32 v112, v112
	v_add_f32_e32 v110, 1.0, v110
	v_rcp_f32_e32 v114, v110
	v_fmamk_f32 v110, v111, 0xbfb8aa3b, v219
	v_add_f32_e32 v112, 1.0, v112
	v_exp_f32_e32 v110, v110
	v_rcp_f32_e32 v116, v112
	v_fmamk_f32 v112, v113, 0xbfb8aa3b, v221
	v_exp_f32_e32 v112, v112
	v_add_f32_e32 v110, 1.0, v110
	v_pk_mul_f32 v[104:105], v[104:105], v[148:149]
	v_rcp_f32_e32 v115, v110
	v_mul_f32_e32 v118, v104, v96
	v_add_f32_e32 v112, 1.0, v112
	v_fmac_f32_e32 v145, v240, v118
	v_mul_f32_e32 v118, v105, v97
	v_rcp_f32_e32 v117, v112
	v_fmac_f32_e32 v145, v241, v118
	v_pk_add_f32 v[110:111], v[114:115], -1.0 op_sel_hi:[1,0]
	v_pk_add_f32 v[112:113], v[116:117], -1.0 op_sel_hi:[1,0]
	v_pk_fma_f32 v[110:111], v[234:235], v[110:111], 1.0 op_sel_hi:[1,1,0]
	v_and_b32_e32 v91, 0xffff0000, v92
	v_pk_mul_f32 v[110:111], v[110:111], v[158:159]
	s_waitcnt lgkmcnt(1)
	v_pk_mul_f32 v[122:123], v[226:227], v[158:159]
	v_mul_f32_e32 v158, v110, v90
	v_pk_fma_f32 v[112:113], v[236:237], v[112:113], 1.0 op_sel_hi:[1,1,0]
	v_lshlrev_b32_e32 v92, 16, v93
	s_waitcnt lgkmcnt(0)
	v_fmac_f32_e32 v145, v242, v158
	v_mul_f32_e32 v118, v111, v91
	v_pk_mul_f32 v[112:113], v[112:113], v[156:157]
	v_fmac_f32_e32 v145, v243, v118
	v_pk_mul_f32 v[118:119], v[228:229], v[156:157]
	v_mul_f32_e32 v156, v112, v92
	v_fmac_f32_e32 v145, v244, v156
	v_and_b32_e32 v93, 0xffff0000, v93
	v_mul_f32_e32 v120, v113, v93
	v_fmac_f32_e32 v145, v245, v120
	v_pk_mul_f32 v[154:155], v[122:123], v[122:123]
	s_waitcnt lgkmcnt(0)
; __device__ __forceinline__ float sigmoidf_(float x) { return __builtin_amdgcn_rcpf(1.0f + __expf(-x)); }
; __device__ __forceinline__ float allreduce8(float x) { x += dppf(x, 0); x += dppf(x, 1); x += dppf(x, 2); return x; }
; __device__ void rw_scan(const Params& p, int l, unsigned char* shm, int item) {
;     ...
; #pragma unroll
;                 for (int e = 0; e < 8; ++e) { const float wa = cst[sub * 8 + e] + (e < 4 ? wl0[e & 3] : wl1[e & 3]), aa = cst[64 + sub * 8 + e] + (e < 4 ? al0[e & 3] : al1[e & 3]);
;                     av[e] = sigmoidf_(aa); dec[e] = __expf(-0.6065306597126334f * sigmoidf_(wa)); kkv[e] = ks_[e] * cst[128 + sub * 8 + e]; ssq += kkv[e] * kkv[e];
;                     kd[e] = ks_[e] * (1.0f + (av[e] - 1.0f) * cst[192 + sub * 8 + e]); bpart += rs_[e] * kd[e] * cst[256 + sub * 8 + e]; }
;                 ssq = allreduce8(ssq); bpart = allreduce8(bpart);
;                 const float inrm = __builtin_amdgcn_rcpf(fmaxf(__builtin_amdgcn_sqrtf(ssq), 1e-12f));
; #pragma unroll
;                 for (int hf = 0; hf < 2; ++hf) {
;                     f32x4 o_r, o_w, o_k, o_a, o_b;
; #pragma unroll
;                     for (int e = 0; e < 4; ++e) { const int ee = hf * 4 + e; const float kk = kkv[ee] * inrm; o_r[e] = rs_[ee]; o_w[e] = dec[ee]; o_k[e] = kd[ee]; o_a[e] = -kk; o_b[e] = kk * av[ee]; }
;                     const int o = ptok * 64 + sub * 8 + hf * 4;
;                     *(f32x4*)(sr + o) = o_r; *(f32x4*)(sw + o) = o_w; *(f32x4*)(sk + o) = o_k; *(f32x4*)(sa + o) = o_a; *(f32x4*)(sb + o) = o_b;
;                 }
;                 if ((sub >> 1) == quarter) { const int o = ptok * 16 + (sub & 1) * 8;
;                     *(f32x4*)(sv + o) = (f32x4){vs_[0], vs_[1], vs_[2], vs_[3]}; *(f32x4*)(sv + o + 4) = (f32x4){vs_[4], vs_[5], vs_[6], vs_[7]}; }
	v_pk_mul_f32 v[146:147], v[222:223], v[146:147]
	v_pk_mul_f32 v[148:149], v[224:225], v[148:149]
	v_pk_mul_f32 v[156:157], v[146:147], v[146:147]
	v_add_f32_dpp v120, v145, v145 quad_perm:[1,0,3,2] row_mask:0xf bank_mask:0xf bound_ctrl:1
	v_pk_mul_f32 v[158:159], v[148:149], v[148:149]
	v_add_f32_e32 v145, v156, v157
	v_add_f32_e32 v145, v145, v158
	v_add_f32_e32 v145, v145, v159
	v_add_f32_e32 v145, v145, v154
	v_pk_mul_f32 v[124:125], v[118:119], v[118:119]
	v_add_f32_e32 v145, v145, v155
	v_fmamk_f32 v98, v98, 0xbfb8aa3b, v206
	v_fmamk_f32 v99, v99, 0xbfb8aa3b, v207
	v_fmamk_f32 v100, v100, 0xbfb8aa3b, v208
	v_fmamk_f32 v101, v101, 0xbfb8aa3b, v209
	v_add_f32_e32 v124, v145, v124
	v_exp_f32_e32 v98, v98
	v_exp_f32_e32 v99, v99
	v_exp_f32_e32 v100, v100
	v_exp_f32_e32 v101, v101
	v_fmamk_f32 v106, v106, 0xbfb8aa3b, v210
	v_fmamk_f32 v107, v107, 0xbfb8aa3b, v211
	v_fmamk_f32 v108, v108, 0xbfb8aa3b, v212
	v_fmamk_f32 v109, v109, 0xbfb8aa3b, v213
	v_add_f32_e32 v124, v124, v125
	v_exp_f32_e32 v106, v106
	v_exp_f32_e32 v107, v107
	v_exp_f32_e32 v108, v108
	v_exp_f32_e32 v109, v109
	v_add_f32_dpp v124, v124, v124 quad_perm:[1,0,3,2] row_mask:0xf bank_mask:0xf bound_ctrl:1
	v_add_f32_e32 v98, 1.0, v98
	v_add_f32_e32 v99, 1.0, v99
	v_add_f32_dpp v124, v124, v124 quad_perm:[2,3,0,1] row_mask:0xf bank_mask:0xf bound_ctrl:1
	v_add_f32_e32 v100, 1.0, v100
	v_add_f32_e32 v101, 1.0, v101
	v_add_f32_dpp v124, v124, v124 row_half_mirror row_mask:0xf bank_mask:0xf bound_ctrl:1
	v_sqrt_f32_e32 v124, v124
	v_rcp_f32_e32 v98, v98
	v_rcp_f32_e32 v99, v99
	v_rcp_f32_e32 v100, v100
	v_rcp_f32_e32 v101, v101
	v_add_f32_e32 v106, 1.0, v106
	v_add_f32_e32 v107, 1.0, v107
	v_add_f32_e32 v108, 1.0, v108
	v_add_f32_e32 v109, 1.0, v109
	v_rcp_f32_e32 v106, v106
	v_rcp_f32_e32 v107, v107
	v_rcp_f32_e32 v108, v108
	v_rcp_f32_e32 v109, v109
	v_max_f32_e32 v124, 0x2b8cbccc, v124
	v_mul_f32_e32 v98, 0xbf60028a, v98
	v_mul_f32_e32 v99, 0xbf60028a, v99
	v_mul_f32_e32 v100, 0xbf60028a, v100
	v_mul_f32_e32 v101, 0xbf60028a, v101
	v_rcp_f32_e32 v124, v124
	s_bitcmp1_b32 s15, 0
	v_mul_f32_e32 v106, 0xbf60028a, v106
	v_mul_f32_e32 v107, 0xbf60028a, v107
	v_mul_f32_e32 v108, 0xbf60028a, v108
	v_mul_f32_e32 v109, 0xbf60028a, v109
	s_cselect_b32 s0, 0xa800, 0
	v_exp_f32_e32 v98, v98
	v_exp_f32_e32 v99, v99
	v_exp_f32_e32 v100, v100
	v_exp_f32_e32 v101, v101
	s_add_i32 s8, s0, 0
	v_exp_f32_e32 v106, v106
	v_exp_f32_e32 v107, v107
	v_exp_f32_e32 v108, v108
	v_exp_f32_e32 v109, v109
	v_add_f32_dpp v120, v120, v120 quad_perm:[2,3,0,1] row_mask:0xf bank_mask:0xf bound_ctrl:1
	v_pk_mul_f32 v[154:155], v[146:147], v[124:125] op_sel_hi:[1,0]
	v_pk_mul_f32 v[156:157], v[148:149], v[124:125] op_sel_hi:[1,0]
	v_lshl_add_u32 v125, v182, 2, s8
	v_mov_b32_dpp v121, v120 row_half_mirror row_mask:0xf bank_mask:0xf bound_ctrl:1
	v_xor_b32_e32 v147, 0x80000000, v155
	v_xor_b32_e32 v146, 0x80000000, v154
	v_xor_b32_e32 v148, 0x80000000, v156
	v_xor_b32_e32 v149, 0x80000000, v157
	v_pk_mul_f32 v[150:151], v[150:151], v[154:155]
	v_pk_mul_f32 v[152:153], v[152:153], v[156:157]
	ds_write_b128 v125, v[94:97]
	ds_write_b128 v125, v[98:101] offset:8192
	ds_write_b128 v125, v[102:105] offset:16384
	ds_write_b128 v125, v[146:149] offset:24576
	ds_write_b128 v125, v[150:153] offset:32768
	v_pk_mul_f32 v[98:99], v[122:123], v[124:125] op_sel_hi:[1,0]
	v_pk_mul_f32 v[100:101], v[118:119], v[124:125] op_sel_hi:[1,0]
	v_xor_b32_e32 v95, 0x80000000, v99
	v_xor_b32_e32 v94, 0x80000000, v98
	v_xor_b32_e32 v96, 0x80000000, v100
	v_xor_b32_e32 v97, 0x80000000, v101
	v_pk_mul_f32 v[98:99], v[114:115], v[98:99]
	v_pk_mul_f32 v[100:101], v[116:117], v[100:101]
	ds_write_b128 v125, v[90:93] offset:16
	ds_write_b128 v125, v[106:109] offset:8208
	ds_write_b128 v125, v[110:113] offset:16400
	ds_write_b128 v125, v[94:97] offset:24592
	ds_write_b128 v125, v[98:101] offset:32784
	s_and_saveexec_b64 s[0:1], s[4:5]
	s_cbranch_execz .LBB0_318
	v_lshlrev_b32_e32 v94, 2, v181
	v_lshlrev_b32_e32 v90, 16, v70
	v_and_b32_e32 v91, 0xffff0000, v70
	v_lshlrev_b32_e32 v92, 16, v71
	v_and_b32_e32 v93, 0xffff0000, v71
	v_add3_u32 v94, s8, v180, v94
	v_lshlrev_b32_e32 v70, 16, v72
	v_and_b32_e32 v71, 0xffff0000, v72
	v_lshlrev_b32_e32 v72, 16, v73
	v_and_b32_e32 v73, 0xffff0000, v73
	ds_write_b128 v94, v[90:93] offset:40960
	ds_write_b128 v94, v[70:73] offset:40976
